# sample-attention PV loop rewritten: 2 keys per iteration with ds_read_b64 P-row reads and scalar fma (same accumulation order), on top of v35 fast grid barrier
# speedup vs baseline: 1.0378x; 1.0118x over previous
; DI void attn_sample(const P& p, char* smem, int s, int h, float lam, float M2) {
;     ...
;     for (int k2 = 0; k2 < nvalid; k2++) {
;       float v = Vl[k2 * 128 + dv];
; #pragma unroll
;       for (int m = 0; m < 2; m++)
; #pragma unroll
;         for (int qq = 0; qq < 4; qq++) {
;           float pp = Ps[(m * 16 + 4 * qg + qq) * 64 + k2];
;           acc[m][qq] += pp * v;
;           ls[m][qq] += pp;
;         }
;     }
.LBB0_748:
	ds_read_b32 v38, v2
	ds_read_b32 v39, v2 offset:512
	ds_read_b64 v[40:41], v36
	ds_read_b64 v[42:43], v36 offset:256
	ds_read_b64 v[44:45], v36 offset:512
	ds_read_b64 v[46:47], v36 offset:768
	ds_read_b64 v[48:49], v36 offset:4096
	ds_read_b64 v[50:51], v36 offset:4352
	ds_read_b64 v[52:53], v36 offset:4608
	ds_read_b64 v[54:55], v36 offset:4864
	s_add_i32 s0, s0, -2
	v_add_u32_e32 v36, 8, v36
	v_add_u32_e32 v2, 0x400, v2
	s_cmp_eq_u32 s0, 0
	s_waitcnt lgkmcnt(7)
	v_fma_f32 v79, v38, v40, v79
	v_add_f32_e32 v83, v83, v40
	s_waitcnt lgkmcnt(6)
	v_fma_f32 v78, v38, v42, v78
	v_add_f32_e32 v82, v82, v42
	s_waitcnt lgkmcnt(5)
	v_fma_f32 v71, v38, v44, v71
	v_add_f32_e32 v75, v75, v44
	s_waitcnt lgkmcnt(4)
	v_fma_f32 v70, v38, v46, v70
	v_add_f32_e32 v74, v74, v46
	s_waitcnt lgkmcnt(3)
	v_fma_f32 v81, v38, v48, v81
	v_add_f32_e32 v77, v77, v48
	s_waitcnt lgkmcnt(2)
	v_fma_f32 v80, v38, v50, v80
	v_add_f32_e32 v76, v76, v50
	s_waitcnt lgkmcnt(1)
	v_fma_f32 v73, v38, v52, v73
	v_add_f32_e32 v69, v69, v52
	s_waitcnt lgkmcnt(0)
	v_fma_f32 v72, v38, v54, v72
	v_add_f32_e32 v68, v68, v54
	v_fma_f32 v79, v39, v41, v79
	v_add_f32_e32 v83, v83, v41
	v_fma_f32 v78, v39, v43, v78
	v_add_f32_e32 v82, v82, v43
	v_fma_f32 v71, v39, v45, v71
	v_add_f32_e32 v75, v75, v45
	v_fma_f32 v70, v39, v47, v70
	v_add_f32_e32 v74, v74, v47
	v_fma_f32 v81, v39, v49, v81
	v_add_f32_e32 v77, v77, v49
	v_fma_f32 v80, v39, v51, v80
	v_add_f32_e32 v76, v76, v51
	v_fma_f32 v73, v39, v53, v73
	v_add_f32_e32 v69, v69, v53
	v_fma_f32 v72, v39, v55, v72
	v_add_f32_e32 v68, v68, v55
	s_cbranch_scc0 .LBB0_748
	s_add_i32 s34, s34, 1
	s_cmp_eq_u32 s34, 17
	s_cbranch_scc1 .LBB0_751
	v_mov_b64_e32 v[38:39], v[6:7]
	v_mov_b64_e32 v[46:47], v[10:11]
	v_mov_b64_e32 v[54:55], v[18:19]
	v_mov_b64_e32 v[62:63], v[26:27]
	v_mov_b64_e32 v[42:43], v[14:15]
	v_mov_b64_e32 v[50:51], v[22:23]
	v_mov_b64_e32 v[58:59], v[30:31]
	v_mov_b64_e32 v[66:67], v[34:35]
	v_mov_b64_e32 v[36:37], v[4:5]
	v_mov_b64_e32 v[44:45], v[8:9]
	v_mov_b64_e32 v[52:53], v[16:17]
	v_mov_b64_e32 v[60:61], v[24:25]
	v_mov_b64_e32 v[40:41], v[12:13]
	v_mov_b64_e32 v[48:49], v[20:21]
	v_mov_b64_e32 v[56:57], v[28:29]
	v_mov_b64_e32 v[64:65], v[32:33]
	s_branch .LBB0_739
